# attention steady loops: half of the second half-step's row-sum adds moved behind the first half-step's exps (one add per exp pair into a spare register); on top of the MODE 1 epilogue edits
# baseline (speedup 1.0000x reference)
.LBB0_396:
	s_mov_b32 s36, s66
	s_mov_b32 s5, s40
	s_mov_b32 s6, s3
	v_lshl_add_u32 v195, s37, 1, v230
	ds_read_b64_tr_b16 v[196:197], v195 offset:24576
	ds_read_b64_tr_b16 v[198:199], v195 offset:25088
	v_add_f32_e32 v96, v64, v65
	v_add_f32_e32 v96, v66, v96
	v_add_f32_e32 v96, v67, v96
	v_add_f32_e32 v96, v68, v96
	v_add_f32_e32 v96, v69, v96
	v_cvt_pk_bf16_f32 v144, v64, v65
	v_cvt_pk_bf16_f32 v145, v66, v67
	s_waitcnt lgkmcnt(9)
	v_mfma_f32_32x32x16_bf16 v[112:127], v[188:191], v[128:131], 0
	ds_read_b64_tr_b16 v[64:65], v195 offset:28672
	ds_read_b64_tr_b16 v[66:67], v195 offset:29184
	v_add_f32_e32 v96, v70, v96
	v_add_f32_e32 v96, v71, v96
	v_add_f32_e32 v96, v72, v96
	v_add_f32_e32 v148, v73, v96
	v_cvt_pk_bf16_f32 v146, v68, v69
	v_cvt_pk_bf16_f32 v147, v70, v71
	s_waitcnt lgkmcnt(10)
	v_mfma_f32_32x32x16_bf16 v[96:111], v[180:183], v[128:131], 0
	ds_read_b64_tr_b16 v[68:69], v195 offset:25600
	ds_read_b64_tr_b16 v[70:71], v195 offset:26112
	v_add_f32_e32 v148, v74, v148
	v_add_f32_e32 v148, v75, v148
	v_add_f32_e32 v148, v76, v148
	v_add_f32_e32 v152, v77, v148
	v_cvt_pk_bf16_f32 v148, v72, v73
	v_cvt_pk_bf16_f32 v149, v74, v75
	s_waitcnt lgkmcnt(11)
	v_mfma_f32_32x32x16_bf16 v[112:127], v[184:187], v[132:135], v[112:127]
	ds_read_b64_tr_b16 v[72:73], v195 offset:29696
	ds_read_b64_tr_b16 v[74:75], v195 offset:30208
	v_add_f32_e32 v150, v78, v152
	v_add_f32_e32 v150, v79, v150
	v_add_f32_e32 v150, v80, v150
	v_add_f32_e32 v152, v81, v150
	v_cvt_pk_bf16_f32 v150, v76, v77
	v_cvt_pk_bf16_f32 v151, v78, v79
	s_waitcnt lgkmcnt(12)
	v_mfma_f32_32x32x16_bf16 v[96:111], v[176:179], v[132:135], v[96:111]
	ds_read_b64_tr_b16 v[76:77], v195 offset:26624
	ds_read_b64_tr_b16 v[78:79], v195 offset:27136
	v_add_f32_e32 v152, v82, v152
	v_add_f32_e32 v152, v83, v152
	v_add_f32_e32 v152, v84, v152
	v_add_f32_e32 v156, v85, v152
	v_cvt_pk_bf16_f32 v152, v80, v81
	v_cvt_pk_bf16_f32 v153, v82, v83
	s_waitcnt lgkmcnt(13)
	v_mfma_f32_32x32x16_bf16 v[112:127], v[172:175], v[136:139], v[112:127]
	ds_read_b64_tr_b16 v[200:201], v195 offset:30720
	ds_read_b64_tr_b16 v[202:203], v195 offset:31232
	v_add_f32_e32 v80, v86, v156
	v_add_f32_e32 v80, v87, v80
	v_add_f32_e32 v80, v88, v80
	v_add_f32_e32 v80, v89, v80
	v_cvt_pk_bf16_f32 v154, v84, v85
	v_cvt_pk_bf16_f32 v155, v86, v87
	s_waitcnt lgkmcnt(14)
	v_mfma_f32_32x32x16_bf16 v[96:111], v[168:171], v[136:139], v[96:111]
	ds_read_b64_tr_b16 v[84:85], v195 offset:27648
	ds_read_b64_tr_b16 v[86:87], v195 offset:28160
	v_add_f32_e32 v80, v90, v80
	v_add_f32_e32 v80, v91, v80
	v_add_f32_e32 v80, v92, v80
	v_add_f32_e32 v80, v93, v80
	v_cvt_pk_bf16_f32 v156, v88, v89
	v_cvt_pk_bf16_f32 v157, v90, v91
	s_waitcnt lgkmcnt(14)
	v_mfma_f32_32x32x16_bf16 v[112:127], v[164:167], v[140:143], v[112:127]
	ds_read_b64_tr_b16 v[88:89], v195 offset:31744
	ds_read_b64_tr_b16 v[90:91], v195 offset:32256
	v_add_f32_e32 v80, v94, v80
	v_add_f32_e32 v80, v95, v80
	v_add_f32_e32 v80, 0, v80
	v_cvt_pk_bf16_f32 v158, v92, v93
	v_cvt_pk_bf16_f32 v159, v94, v95
	v_mfma_f32_32x32x16_bf16 v[96:111], v[160:163], v[140:143], v[96:111]
	s_add_i32 s3, s3, s2
	v_add_f32_e32 v188, v231, v80
	s_mov_b32 m0, s3
	s_add_u32 s100, s98, s72
	s_addc_u32 s101, s99, s73
	global_load_lds_dwordx4 v238, s[100:101]
	s_lshl_b32 s3, s66, 1
	s_add_i32 s3, s3, s35
	s_mov_b32 m0, s3
	s_add_u32 s100, s98, s74
	s_addc_u32 s101, s99, s75
	global_load_lds_dwordx4 v239, s[100:101]
	s_addk_i32 s3, 0x2000
	s_mov_b32 m0, s3
	s_add_u32 s100, s98, s76
	s_addc_u32 s101, s99, s77
	global_load_lds_dwordx4 v239, s[100:101]
	s_waitcnt lgkmcnt(14)
	v_mfma_f32_32x32x16_bf16 v[0:15], v[144:147], v[196:199], v[0:15]
	v_exp_f32_e32 v112, v112
	v_exp_f32_e32 v113, v113
	v_mov_b32_e32 v255, v112
	ds_read_b64_tr_b16 v[92:93], v195 offset:32768
	ds_read_b64_tr_b16 v[94:95], v195 offset:33280
	s_waitcnt lgkmcnt(14)
	v_mfma_f32_32x32x16_bf16 v[16:31], v[144:147], v[64:67], v[16:31]
	v_exp_f32_e32 v114, v114
	v_exp_f32_e32 v115, v115
	v_add_f32_e32 v255, v114, v255
	ds_read_b64_tr_b16 v[196:197], v195 offset:36864
	ds_read_b64_tr_b16 v[198:199], v195 offset:37376
	v_add_u32_e32 v160, s36, v229
	ds_read_b128 v[64:67], v160
	ds_read_b128 v[80:83], v160 offset:512
	s_waitcnt lgkmcnt(14)
	v_mfma_f32_32x32x16_bf16 v[0:15], v[148:151], v[68:71], v[0:15]
	v_exp_f32_e32 v116, v116
	v_exp_f32_e32 v117, v117
	v_add_f32_e32 v255, v116, v255
	ds_read_b64_tr_b16 v[68:69], v195 offset:33792
	ds_read_b64_tr_b16 v[70:71], v195 offset:34304
	ds_read_b128 v[180:183], v160 offset:2048
	ds_read_b128 v[176:179], v160 offset:2560
	v_mfma_f32_32x32x16_bf16 v[16:31], v[148:151], v[72:75], v[16:31]
	v_exp_f32_e32 v118, v118
	v_exp_f32_e32 v119, v119
	v_add_f32_e32 v255, v118, v255
	ds_read_b64_tr_b16 v[72:73], v195 offset:37888
	ds_read_b64_tr_b16 v[74:75], v195 offset:38400
	ds_read_b128 v[172:175], v160 offset:4096
	ds_read_b128 v[168:171], v160 offset:4608
	s_waitcnt lgkmcnt(14)
	v_mfma_f32_32x32x16_bf16 v[0:15], v[152:155], v[76:79], v[0:15]
	v_exp_f32_e32 v120, v120
	v_exp_f32_e32 v121, v121
	v_add_f32_e32 v255, v120, v255
	ds_read_b64_tr_b16 v[76:77], v195 offset:34816
	ds_read_b64_tr_b16 v[78:79], v195 offset:35328
	ds_read_b128 v[164:167], v160 offset:6144
	ds_read_b128 v[160:163], v160 offset:6656
	v_mfma_f32_32x32x16_bf16 v[16:31], v[152:155], v[200:203], v[16:31]
	v_exp_f32_e32 v122, v122
	v_exp_f32_e32 v123, v123
	v_add_f32_e32 v255, v122, v255
	ds_read_b64_tr_b16 v[200:201], v195 offset:38912
	ds_read_b64_tr_b16 v[202:203], v195 offset:39424
	v_mfma_f32_32x32x16_bf16 v[0:15], v[156:159], v[84:87], v[0:15]
	v_exp_f32_e32 v124, v124
	v_exp_f32_e32 v125, v125
	v_add_f32_e32 v255, v124, v255
	ds_read_b64_tr_b16 v[84:85], v195 offset:35840
	ds_read_b64_tr_b16 v[86:87], v195 offset:36352
	v_mfma_f32_32x32x16_bf16 v[16:31], v[156:159], v[88:91], v[16:31]
	v_exp_f32_e32 v126, v126
	v_exp_f32_e32 v127, v127
	s_nop 0
	v_add_f32_e32 v255, v127, v255
	ds_read_b64_tr_b16 v[88:89], v195 offset:39936
	ds_read_b64_tr_b16 v[90:91], v195 offset:40448
	s_waitcnt lgkmcnt(14)
	v_mfma_f32_32x32x16_bf16 v[32:47], v[144:147], v[92:95], v[32:47]
	v_exp_f32_e32 v96, v96
	v_exp_f32_e32 v97, v97
	v_add_f32_e32 v255, v96, v255
	v_mfma_f32_32x32x16_bf16 v[48:63], v[144:147], v[196:199], v[48:63]
	v_exp_f32_e32 v98, v98
	v_exp_f32_e32 v99, v99
	v_add_f32_e32 v255, v98, v255
	v_mfma_f32_32x32x16_bf16 v[32:47], v[148:151], v[68:71], v[32:47]
	v_exp_f32_e32 v100, v100
	v_exp_f32_e32 v101, v101
	v_add_f32_e32 v255, v100, v255
	s_waitcnt lgkmcnt(12)
	v_mfma_f32_32x32x16_bf16 v[48:63], v[148:151], v[72:75], v[48:63]
	v_exp_f32_e32 v102, v102
	v_exp_f32_e32 v103, v103
	s_nop 0
	v_add_f32_e32 v255, v103, v255
	s_waitcnt lgkmcnt(8)
	v_mfma_f32_32x32x16_bf16 v[32:47], v[152:155], v[76:79], v[32:47]
	v_exp_f32_e32 v104, v104
	v_exp_f32_e32 v105, v105
	v_add_f32_e32 v255, v104, v255
	s_waitcnt lgkmcnt(4)
	v_mfma_f32_32x32x16_bf16 v[48:63], v[152:155], v[200:203], v[48:63]
	v_exp_f32_e32 v106, v106
	v_exp_f32_e32 v107, v107
	v_add_f32_e32 v255, v106, v255
	s_waitcnt lgkmcnt(2)
	v_mfma_f32_32x32x16_bf16 v[32:47], v[156:159], v[84:87], v[32:47]
	v_exp_f32_e32 v108, v108
	v_exp_f32_e32 v109, v109
	v_add_f32_e32 v255, v108, v255
	s_waitcnt lgkmcnt(0)
	v_mfma_f32_32x32x16_bf16 v[48:63], v[156:159], v[88:91], v[48:63]
	v_exp_f32_e32 v110, v110
	v_exp_f32_e32 v111, v111
	s_nop 0
	v_add_f32_e32 v255, v111, v255
	s_waitcnt vmcnt(3) lgkmcnt(0)
	s_barrier
	s_add_i32 s3, s66, 0x2000
	s_cmpk_lg_i32 s66, 0x4000
	s_cselect_b32 s3, s3, 0
	v_lshl_add_u32 v195, s6, 1, v230
	ds_read_b64_tr_b16 v[196:197], v195 offset:24576
	ds_read_b64_tr_b16 v[198:199], v195 offset:25088
	v_add_f32_e32 v68, v113, v255
	v_add_f32_e32 v68, v115, v68
	v_add_f32_e32 v84, v117, v68
	v_mfma_f32_32x32x16_bf16 v[64:79], v[64:67], v[128:131], 0
	v_cvt_pk_bf16_f32 v144, v112, v113
	v_cvt_pk_bf16_f32 v145, v114, v115
	ds_read_b64_tr_b16 v[112:113], v195 offset:28672
	ds_read_b64_tr_b16 v[114:115], v195 offset:29184
	v_add_f32_e32 v84, v119, v84
	v_add_f32_e32 v148, v121, v84
	v_mfma_f32_32x32x16_bf16 v[80:95], v[80:83], v[128:131], 0
	v_cvt_pk_bf16_f32 v146, v116, v117
	v_cvt_pk_bf16_f32 v147, v118, v119
	ds_read_b64_tr_b16 v[116:117], v195 offset:25600
	ds_read_b64_tr_b16 v[118:119], v195 offset:26112
	v_mfma_f32_32x32x16_bf16 v[64:79], v[180:183], v[132:135], v[64:79]
	v_add_f32_e32 v148, v123, v148
	v_add_f32_e32 v152, v125, v148
	v_cvt_pk_bf16_f32 v148, v120, v121
	v_cvt_pk_bf16_f32 v149, v122, v123
	ds_read_b64_tr_b16 v[120:121], v195 offset:29696
	ds_read_b64_tr_b16 v[122:123], v195 offset:30208
	v_mfma_f32_32x32x16_bf16 v[80:95], v[176:179], v[132:135], v[80:95]
	v_add_f32_e32 v150, v126, v152
	v_add_f32_e32 v152, v97, v150
	v_cvt_pk_bf16_f32 v150, v124, v125
	v_cvt_pk_bf16_f32 v151, v126, v127
	ds_read_b64_tr_b16 v[124:125], v195 offset:26624
	ds_read_b64_tr_b16 v[126:127], v195 offset:27136
	v_mfma_f32_32x32x16_bf16 v[64:79], v[172:175], v[136:139], v[64:79]
	v_add_f32_e32 v152, v99, v152
	v_add_f32_e32 v156, v101, v152
	v_cvt_pk_bf16_f32 v152, v96, v97
	v_cvt_pk_bf16_f32 v153, v98, v99
	ds_read_b64_tr_b16 v[96:97], v195 offset:30720
	ds_read_b64_tr_b16 v[98:99], v195 offset:31232
	v_mfma_f32_32x32x16_bf16 v[80:95], v[168:171], v[136:139], v[80:95]
	v_add_f32_e32 v154, v102, v156
	v_add_f32_e32 v156, v105, v154
	v_cvt_pk_bf16_f32 v154, v100, v101
	v_cvt_pk_bf16_f32 v155, v102, v103
	ds_read_b64_tr_b16 v[100:101], v195 offset:27648
	ds_read_b64_tr_b16 v[102:103], v195 offset:28160
	v_mfma_f32_32x32x16_bf16 v[64:79], v[164:167], v[140:143], v[64:79]
	v_add_f32_e32 v156, v107, v156
	v_add_f32_e32 v164, v109, v156
	v_cvt_pk_bf16_f32 v156, v104, v105
	v_cvt_pk_bf16_f32 v157, v106, v107
	ds_read_b64_tr_b16 v[104:105], v195 offset:31744
	ds_read_b64_tr_b16 v[106:107], v195 offset:32256
	v_mfma_f32_32x32x16_bf16 v[80:95], v[160:163], v[140:143], v[80:95]
	v_add_f32_e32 v158, v110, v164
	v_add_f32_e32 v160, 0, v158
	v_cvt_pk_bf16_f32 v158, v108, v109
	v_cvt_pk_bf16_f32 v159, v110, v111
	s_add_i32 s6, s66, s2
	s_mov_b32 m0, s6
	s_add_u32 s100, s98, s78
	s_addc_u32 s101, s99, s79
	global_load_lds_dwordx4 v238, s[100:101]
	s_lshl_b32 s6, s3, 1
	s_add_i32 s6, s6, s35
	s_mov_b32 m0, s6
	s_add_u32 s100, s98, s80
	s_addc_u32 s101, s99, s81
	global_load_lds_dwordx4 v239, s[100:101]
	s_addk_i32 s6, 0x2000
	s_mov_b32 m0, s6
	s_add_u32 s100, s98, s82
	s_addc_u32 s101, s99, s83
	global_load_lds_dwordx4 v239, s[100:101]
	v_add_f32_e32 v231, v188, v160
	s_waitcnt lgkmcnt(14)
	v_mfma_f32_32x32x16_bf16 v[0:15], v[144:147], v[196:199], v[0:15]
	v_exp_f32_e32 v64, v64
	v_exp_f32_e32 v65, v65
	ds_read_b64_tr_b16 v[108:109], v195 offset:32768
	ds_read_b64_tr_b16 v[110:111], v195 offset:33280
	s_waitcnt lgkmcnt(14)
	v_mfma_f32_32x32x16_bf16 v[16:31], v[144:147], v[112:115], v[16:31]
	v_exp_f32_e32 v66, v66
	v_exp_f32_e32 v67, v67
	ds_read_b64_tr_b16 v[112:113], v195 offset:36864
	ds_read_b64_tr_b16 v[114:115], v195 offset:37376
	v_add_u32_e32 v160, s3, v229
	ds_read_b128 v[188:191], v160
	ds_read_b128 v[180:183], v160 offset:512
	s_waitcnt lgkmcnt(14)
	v_mfma_f32_32x32x16_bf16 v[0:15], v[148:151], v[116:119], v[0:15]
	v_exp_f32_e32 v68, v68
	v_exp_f32_e32 v69, v69
	ds_read_b64_tr_b16 v[116:117], v195 offset:33792
	ds_read_b64_tr_b16 v[118:119], v195 offset:34304
	ds_read_b128 v[184:187], v160 offset:2048
	ds_read_b128 v[176:179], v160 offset:2560
	v_mfma_f32_32x32x16_bf16 v[16:31], v[148:151], v[120:123], v[16:31]
	v_exp_f32_e32 v70, v70
	v_exp_f32_e32 v71, v71
	ds_read_b64_tr_b16 v[120:121], v195 offset:37888
	ds_read_b64_tr_b16 v[122:123], v195 offset:38400
	ds_read_b128 v[172:175], v160 offset:4096
	ds_read_b128 v[168:171], v160 offset:4608
	s_waitcnt lgkmcnt(14)
	v_mfma_f32_32x32x16_bf16 v[0:15], v[152:155], v[124:127], v[0:15]
	v_exp_f32_e32 v72, v72
	v_exp_f32_e32 v73, v73
	ds_read_b64_tr_b16 v[124:125], v195 offset:34816
	ds_read_b64_tr_b16 v[126:127], v195 offset:35328
	ds_read_b128 v[164:167], v160 offset:6144
	ds_read_b128 v[160:163], v160 offset:6656
	v_mfma_f32_32x32x16_bf16 v[16:31], v[152:155], v[96:99], v[16:31]
	v_exp_f32_e32 v74, v74
	v_exp_f32_e32 v75, v75
	ds_read_b64_tr_b16 v[96:97], v195 offset:38912
	ds_read_b64_tr_b16 v[98:99], v195 offset:39424
	v_mfma_f32_32x32x16_bf16 v[0:15], v[156:159], v[100:103], v[0:15]
	v_exp_f32_e32 v76, v76
	v_exp_f32_e32 v77, v77
	ds_read_b64_tr_b16 v[100:101], v195 offset:35840
	ds_read_b64_tr_b16 v[102:103], v195 offset:36352
	v_mfma_f32_32x32x16_bf16 v[16:31], v[156:159], v[104:107], v[16:31]
	v_exp_f32_e32 v78, v78
	v_exp_f32_e32 v79, v79
	ds_read_b64_tr_b16 v[104:105], v195 offset:39936
	ds_read_b64_tr_b16 v[106:107], v195 offset:40448
	s_waitcnt lgkmcnt(14)
	v_mfma_f32_32x32x16_bf16 v[32:47], v[144:147], v[108:111], v[32:47]
	v_exp_f32_e32 v80, v80
	v_exp_f32_e32 v81, v81
	v_mfma_f32_32x32x16_bf16 v[48:63], v[144:147], v[112:115], v[48:63]
	v_exp_f32_e32 v82, v82
	v_exp_f32_e32 v83, v83
	v_mfma_f32_32x32x16_bf16 v[32:47], v[148:151], v[116:119], v[32:47]
	v_exp_f32_e32 v84, v84
	v_exp_f32_e32 v85, v85
	s_waitcnt lgkmcnt(12)
	v_mfma_f32_32x32x16_bf16 v[48:63], v[148:151], v[120:123], v[48:63]
	v_exp_f32_e32 v86, v86
	v_exp_f32_e32 v87, v87
	s_waitcnt lgkmcnt(8)
	v_mfma_f32_32x32x16_bf16 v[32:47], v[152:155], v[124:127], v[32:47]
	v_exp_f32_e32 v88, v88
	v_exp_f32_e32 v89, v89
	s_waitcnt lgkmcnt(4)
	v_mfma_f32_32x32x16_bf16 v[48:63], v[152:155], v[96:99], v[48:63]
	v_exp_f32_e32 v90, v90
	v_exp_f32_e32 v91, v91
	s_waitcnt lgkmcnt(2)
	v_mfma_f32_32x32x16_bf16 v[32:47], v[156:159], v[100:103], v[32:47]
	v_exp_f32_e32 v92, v92
	v_exp_f32_e32 v93, v93
	s_waitcnt lgkmcnt(0)
	v_mfma_f32_32x32x16_bf16 v[48:63], v[156:159], v[104:107], v[48:63]
	v_exp_f32_e32 v94, v94
	v_exp_f32_e32 v95, v95
	s_add_i32 s6, s3, 0x2000
	s_cmpk_lg_i32 s3, 0x4000
	s_cselect_b32 s66, s6, 0
	s_add_i32 s40, s40, 2
	s_waitcnt vmcnt(3) lgkmcnt(0)
	s_barrier
	s_add_u32 s38, s38, 0x20000
	s_addc_u32 s39, s39, 0
	s_add_u32 s98, s98, 0x20000
	s_addc_u32 s99, s99, 0
	s_cmp_gt_u32 s40, s57
	s_mov_b32 s37, s36
	s_cbranch_scc0 .LBB0_396
	s_add_i32 s6, s5, -3
	s_xor_b64 s[94:95], s[0:1], -1
	s_cmp_lt_u32 s6, s57
	s_mov_b64 s[0:1], -1
	s_cbranch_scc1 .LBB0_399

.LBB0_439:
	s_mov_b32 s36, s66
	s_mov_b32 s6, s39
	s_mov_b32 s37, s59
	v_lshl_add_u32 v221, s38, 1, v232
	ds_read_b64_tr_b16 v[196:197], v221 offset:24576
	ds_read_b64_tr_b16 v[198:199], v221 offset:25088
	v_add_f32_e32 v96, v80, v81
	v_add_f32_e32 v96, v82, v96
	v_add_f32_e32 v96, v83, v96
	v_add_f32_e32 v96, v84, v96
	v_add_f32_e32 v96, v85, v96
	v_cvt_pk_bf16_f32 v144, v80, v81
	v_cvt_pk_bf16_f32 v145, v82, v83
	s_waitcnt lgkmcnt(9)
	v_mfma_f32_32x32x16_bf16 v[112:127], v[188:191], v[128:131], 0
	ds_read_b64_tr_b16 v[80:81], v221 offset:28672
	ds_read_b64_tr_b16 v[82:83], v221 offset:29184
	v_add_f32_e32 v96, v86, v96
	v_add_f32_e32 v96, v87, v96
	v_add_f32_e32 v96, v88, v96
	v_add_f32_e32 v148, v89, v96
	v_cvt_pk_bf16_f32 v146, v84, v85
	v_cvt_pk_bf16_f32 v147, v86, v87
	s_waitcnt lgkmcnt(10)
	v_mfma_f32_32x32x16_bf16 v[96:111], v[180:183], v[128:131], 0
	ds_read_b64_tr_b16 v[84:85], v221 offset:25600
	ds_read_b64_tr_b16 v[86:87], v221 offset:26112
	v_add_f32_e32 v148, v90, v148
	v_add_f32_e32 v148, v91, v148
	v_add_f32_e32 v148, v92, v148
	v_add_f32_e32 v152, v93, v148
	v_cvt_pk_bf16_f32 v148, v88, v89
	v_cvt_pk_bf16_f32 v149, v90, v91
	s_waitcnt lgkmcnt(11)
	v_mfma_f32_32x32x16_bf16 v[112:127], v[184:187], v[132:135], v[112:127]
	ds_read_b64_tr_b16 v[88:89], v221 offset:29696
	ds_read_b64_tr_b16 v[90:91], v221 offset:30208
	v_add_f32_e32 v150, v94, v152
	v_add_f32_e32 v150, v95, v150
	v_add_f32_e32 v150, v64, v150
	v_add_f32_e32 v152, v65, v150
	v_cvt_pk_bf16_f32 v150, v92, v93
	v_cvt_pk_bf16_f32 v151, v94, v95
	s_waitcnt lgkmcnt(12)
	v_mfma_f32_32x32x16_bf16 v[96:111], v[176:179], v[132:135], v[96:111]
	ds_read_b64_tr_b16 v[92:93], v221 offset:26624
	ds_read_b64_tr_b16 v[94:95], v221 offset:27136
	v_add_f32_e32 v152, v66, v152
	v_add_f32_e32 v152, v67, v152
	v_add_f32_e32 v152, v68, v152
	v_add_f32_e32 v156, v69, v152
	v_cvt_pk_bf16_f32 v152, v64, v65
	v_cvt_pk_bf16_f32 v153, v66, v67
	s_waitcnt lgkmcnt(13)
	v_mfma_f32_32x32x16_bf16 v[112:127], v[172:175], v[136:139], v[112:127]
	ds_read_b64_tr_b16 v[200:201], v221 offset:30720
	ds_read_b64_tr_b16 v[202:203], v221 offset:31232
	v_add_f32_e32 v64, v70, v156
	v_add_f32_e32 v64, v71, v64
	v_add_f32_e32 v64, v72, v64
	v_add_f32_e32 v64, v73, v64
	v_cvt_pk_bf16_f32 v154, v68, v69
	v_cvt_pk_bf16_f32 v155, v70, v71
	s_waitcnt lgkmcnt(14)
	v_mfma_f32_32x32x16_bf16 v[96:111], v[168:171], v[136:139], v[96:111]
	ds_read_b64_tr_b16 v[208:209], v221 offset:27648
	ds_read_b64_tr_b16 v[210:211], v221 offset:28160
	v_add_f32_e32 v64, v74, v64
	v_add_f32_e32 v64, v75, v64
	v_add_f32_e32 v64, v76, v64
	v_add_f32_e32 v64, v77, v64
	v_cvt_pk_bf16_f32 v156, v72, v73
	v_cvt_pk_bf16_f32 v157, v74, v75
	s_waitcnt lgkmcnt(14)
	v_mfma_f32_32x32x16_bf16 v[112:127], v[164:167], v[140:143], v[112:127]
	ds_read_b64_tr_b16 v[72:73], v221 offset:31744
	ds_read_b64_tr_b16 v[74:75], v221 offset:32256
	v_add_f32_e32 v64, v78, v64
	v_add_f32_e32 v64, v79, v64
	v_add_f32_e32 v64, 0, v64
	v_cvt_pk_bf16_f32 v158, v76, v77
	v_cvt_pk_bf16_f32 v159, v78, v79
	v_mfma_f32_32x32x16_bf16 v[96:111], v[160:163], v[140:143], v[96:111]
	s_add_i32 s38, s59, s3
	v_add_f32_e32 v188, v233, v64
	s_mov_b32 m0, s38
	s_add_u32 s100, s98, s72
	s_addc_u32 s101, s99, s73
	global_load_lds_dwordx4 v238, s[100:101]
	s_lshl_b32 s38, s66, 1
	s_add_i32 s38, s38, s35
	s_mov_b32 m0, s38
	s_add_u32 s100, s98, s74
	s_addc_u32 s101, s99, s75
	global_load_lds_dwordx4 v239, s[100:101]
	s_addk_i32 s38, 0x2000
	s_mov_b32 m0, s38
	s_add_u32 s100, s98, s76
	s_addc_u32 s101, s99, s77
	global_load_lds_dwordx4 v239, s[100:101]
	s_waitcnt lgkmcnt(14)
	v_mfma_f32_32x32x16_bf16 v[48:63], v[144:147], v[196:199], v[48:63]
	v_exp_f32_e32 v112, v112
	v_exp_f32_e32 v113, v113
	v_mov_b32_e32 v255, v112
	ds_read_b64_tr_b16 v[76:77], v221 offset:32768
	ds_read_b64_tr_b16 v[78:79], v221 offset:33280
	s_waitcnt lgkmcnt(14)
	v_mfma_f32_32x32x16_bf16 v[32:47], v[144:147], v[80:83], v[32:47]
	v_exp_f32_e32 v114, v114
	v_exp_f32_e32 v115, v115
	v_add_f32_e32 v255, v114, v255
	ds_read_b64_tr_b16 v[80:81], v221 offset:36864
	ds_read_b64_tr_b16 v[82:83], v221 offset:37376
	v_add_u32_e32 v160, s36, v231
	ds_read_b128 v[68:71], v160
	ds_read_b128 v[64:67], v160 offset:512
	s_waitcnt lgkmcnt(14)
	v_mfma_f32_32x32x16_bf16 v[48:63], v[148:151], v[84:87], v[48:63]
	v_exp_f32_e32 v116, v116
	v_exp_f32_e32 v117, v117
	v_add_f32_e32 v255, v116, v255
	ds_read_b64_tr_b16 v[84:85], v221 offset:33792
	ds_read_b64_tr_b16 v[86:87], v221 offset:34304
	ds_read_b128 v[180:183], v160 offset:2048
	ds_read_b128 v[176:179], v160 offset:2560
	v_mfma_f32_32x32x16_bf16 v[32:47], v[148:151], v[88:91], v[32:47]
	v_exp_f32_e32 v118, v118
	v_exp_f32_e32 v119, v119
	s_nop 0
	v_add_f32_e32 v255, v119, v255
	ds_read_b64_tr_b16 v[88:89], v221 offset:37888
	ds_read_b64_tr_b16 v[90:91], v221 offset:38400
	ds_read_b128 v[172:175], v160 offset:4096
	ds_read_b128 v[168:171], v160 offset:4608
	s_waitcnt lgkmcnt(14)
	v_mfma_f32_32x32x16_bf16 v[48:63], v[152:155], v[92:95], v[48:63]
	v_exp_f32_e32 v120, v120
	v_exp_f32_e32 v121, v121
	v_add_f32_e32 v255, v120, v255
	ds_read_b64_tr_b16 v[92:93], v221 offset:34816
	ds_read_b64_tr_b16 v[94:95], v221 offset:35328
	ds_read_b128 v[164:167], v160 offset:6144
	ds_read_b128 v[160:163], v160 offset:6656
	v_mfma_f32_32x32x16_bf16 v[32:47], v[152:155], v[200:203], v[32:47]
	v_exp_f32_e32 v122, v122
	v_exp_f32_e32 v123, v123
	v_add_f32_e32 v255, v122, v255
	ds_read_b64_tr_b16 v[196:197], v221 offset:38912
	ds_read_b64_tr_b16 v[198:199], v221 offset:39424
	v_mfma_f32_32x32x16_bf16 v[48:63], v[156:159], v[208:211], v[48:63]
	v_exp_f32_e32 v124, v124
	v_exp_f32_e32 v125, v125
	v_add_f32_e32 v255, v124, v255
	ds_read_b64_tr_b16 v[200:201], v221 offset:35840
	ds_read_b64_tr_b16 v[202:203], v221 offset:36352
	v_mfma_f32_32x32x16_bf16 v[32:47], v[156:159], v[72:75], v[32:47]
	v_exp_f32_e32 v126, v126
	v_exp_f32_e32 v127, v127
	s_nop 0
	v_add_f32_e32 v255, v127, v255
	ds_read_b64_tr_b16 v[72:73], v221 offset:39936
	ds_read_b64_tr_b16 v[74:75], v221 offset:40448
	s_waitcnt lgkmcnt(14)
	v_mfma_f32_32x32x16_bf16 v[16:31], v[144:147], v[76:79], v[16:31]
	v_exp_f32_e32 v96, v96
	v_exp_f32_e32 v97, v97
	v_add_f32_e32 v255, v96, v255
	v_mfma_f32_32x32x16_bf16 v[0:15], v[144:147], v[80:83], v[0:15]
	v_exp_f32_e32 v98, v98
	v_exp_f32_e32 v99, v99
	v_add_f32_e32 v255, v98, v255
	v_mfma_f32_32x32x16_bf16 v[16:31], v[148:151], v[84:87], v[16:31]
	v_exp_f32_e32 v100, v100
	v_exp_f32_e32 v101, v101
	v_add_f32_e32 v255, v100, v255
	s_waitcnt lgkmcnt(12)
	v_mfma_f32_32x32x16_bf16 v[0:15], v[148:151], v[88:91], v[0:15]
	v_exp_f32_e32 v102, v102
	v_exp_f32_e32 v103, v103
	s_nop 0
	v_add_f32_e32 v255, v103, v255
	s_waitcnt lgkmcnt(8)
	v_mfma_f32_32x32x16_bf16 v[16:31], v[152:155], v[92:95], v[16:31]
	v_exp_f32_e32 v104, v104
	v_exp_f32_e32 v105, v105
	v_add_f32_e32 v255, v104, v255
	s_waitcnt lgkmcnt(4)
	v_mfma_f32_32x32x16_bf16 v[0:15], v[152:155], v[196:199], v[0:15]
	v_exp_f32_e32 v106, v106
	v_exp_f32_e32 v107, v107
	v_add_f32_e32 v255, v106, v255
	s_waitcnt lgkmcnt(2)
	v_mfma_f32_32x32x16_bf16 v[16:31], v[156:159], v[200:203], v[16:31]
	v_exp_f32_e32 v108, v108
	v_exp_f32_e32 v109, v109
	v_add_f32_e32 v255, v108, v255
	s_waitcnt lgkmcnt(0)
	v_mfma_f32_32x32x16_bf16 v[0:15], v[156:159], v[72:75], v[0:15]
	v_exp_f32_e32 v110, v110
	v_exp_f32_e32 v111, v111
	s_nop 0
	v_add_f32_e32 v255, v111, v255
	s_waitcnt vmcnt(3) lgkmcnt(0)
	s_barrier
	s_add_i32 s38, s66, 0x2000
	s_cmpk_lg_i32 s66, 0x4000
	s_cselect_b32 s59, s38, 0
	v_lshl_add_u32 v200, s37, 1, v232
	ds_read_b64_tr_b16 v[196:197], v200 offset:24576
	ds_read_b64_tr_b16 v[198:199], v200 offset:25088
	v_mfma_f32_32x32x16_bf16 v[80:95], v[68:71], v[128:131], 0
	v_add_f32_e32 v72, v113, v255
	v_add_f32_e32 v72, v115, v72
	v_add_f32_e32 v72, v117, v72
	v_cvt_pk_bf16_f32 v144, v112, v113
	v_cvt_pk_bf16_f32 v145, v114, v115
	ds_read_b64_tr_b16 v[112:113], v200 offset:28672
	ds_read_b64_tr_b16 v[114:115], v200 offset:29184
	v_add_f32_e32 v68, v118, v72
	v_add_f32_e32 v148, v121, v68
	v_mfma_f32_32x32x16_bf16 v[64:79], v[64:67], v[128:131], 0
	v_cvt_pk_bf16_f32 v146, v116, v117
	v_cvt_pk_bf16_f32 v147, v118, v119
	ds_read_b64_tr_b16 v[116:117], v200 offset:25600
	ds_read_b64_tr_b16 v[118:119], v200 offset:26112
	v_mfma_f32_32x32x16_bf16 v[80:95], v[180:183], v[132:135], v[80:95]
	v_add_f32_e32 v148, v123, v148
	v_add_f32_e32 v152, v125, v148
	v_cvt_pk_bf16_f32 v148, v120, v121
	v_cvt_pk_bf16_f32 v149, v122, v123
	ds_read_b64_tr_b16 v[120:121], v200 offset:29696
	ds_read_b64_tr_b16 v[122:123], v200 offset:30208
	v_mfma_f32_32x32x16_bf16 v[64:79], v[176:179], v[132:135], v[64:79]
	v_add_f32_e32 v150, v126, v152
	v_add_f32_e32 v152, v97, v150
	v_cvt_pk_bf16_f32 v150, v124, v125
	v_cvt_pk_bf16_f32 v151, v126, v127
	ds_read_b64_tr_b16 v[124:125], v200 offset:26624
	ds_read_b64_tr_b16 v[126:127], v200 offset:27136
	v_mfma_f32_32x32x16_bf16 v[80:95], v[172:175], v[136:139], v[80:95]
	v_add_f32_e32 v152, v99, v152
	v_add_f32_e32 v156, v101, v152
	v_cvt_pk_bf16_f32 v152, v96, v97
	v_cvt_pk_bf16_f32 v153, v98, v99
	ds_read_b64_tr_b16 v[96:97], v200 offset:30720
	ds_read_b64_tr_b16 v[98:99], v200 offset:31232
	v_mfma_f32_32x32x16_bf16 v[64:79], v[168:171], v[136:139], v[64:79]
	v_add_f32_e32 v154, v102, v156
	v_add_f32_e32 v156, v105, v154
	v_cvt_pk_bf16_f32 v154, v100, v101
	v_cvt_pk_bf16_f32 v155, v102, v103
	ds_read_b64_tr_b16 v[100:101], v200 offset:27648
	ds_read_b64_tr_b16 v[102:103], v200 offset:28160
	v_mfma_f32_32x32x16_bf16 v[80:95], v[164:167], v[140:143], v[80:95]
	v_add_f32_e32 v156, v107, v156
	v_add_f32_e32 v164, v109, v156
	v_cvt_pk_bf16_f32 v156, v104, v105
	v_cvt_pk_bf16_f32 v157, v106, v107
	ds_read_b64_tr_b16 v[104:105], v200 offset:31744
	ds_read_b64_tr_b16 v[106:107], v200 offset:32256
	v_mfma_f32_32x32x16_bf16 v[64:79], v[160:163], v[140:143], v[64:79]
	v_add_f32_e32 v158, v110, v164
	v_add_f32_e32 v160, 0, v158
	v_cvt_pk_bf16_f32 v158, v108, v109
	v_cvt_pk_bf16_f32 v159, v110, v111
	s_add_i32 s37, s66, s3
	s_mov_b32 m0, s37
	s_add_u32 s100, s98, s78
	s_addc_u32 s101, s99, s79
	global_load_lds_dwordx4 v238, s[100:101]
	s_lshl_b32 s37, s59, 1
	s_add_i32 s37, s37, s35
	s_mov_b32 m0, s37
	s_add_u32 s100, s98, s80
	s_addc_u32 s101, s99, s81
	global_load_lds_dwordx4 v239, s[100:101]
	s_addk_i32 s37, 0x2000
	s_mov_b32 m0, s37
	s_add_u32 s100, s98, s82
	s_addc_u32 s101, s99, s83
	global_load_lds_dwordx4 v239, s[100:101]
	v_add_f32_e32 v233, v188, v160
	s_waitcnt lgkmcnt(14)
	v_mfma_f32_32x32x16_bf16 v[48:63], v[144:147], v[196:199], v[48:63]
	v_exp_f32_e32 v80, v80
	v_exp_f32_e32 v81, v81
	ds_read_b64_tr_b16 v[108:109], v200 offset:32768
	ds_read_b64_tr_b16 v[110:111], v200 offset:33280
	s_waitcnt lgkmcnt(14)
	v_mfma_f32_32x32x16_bf16 v[32:47], v[144:147], v[112:115], v[32:47]
	v_exp_f32_e32 v82, v82
	v_exp_f32_e32 v83, v83
	ds_read_b64_tr_b16 v[112:113], v200 offset:36864
	ds_read_b64_tr_b16 v[114:115], v200 offset:37376
	v_add_u32_e32 v160, s59, v231
	ds_read_b128 v[188:191], v160
	ds_read_b128 v[180:183], v160 offset:512
	s_waitcnt lgkmcnt(14)
	v_mfma_f32_32x32x16_bf16 v[48:63], v[148:151], v[116:119], v[48:63]
	v_exp_f32_e32 v84, v84
	v_exp_f32_e32 v85, v85
	ds_read_b64_tr_b16 v[116:117], v200 offset:33792
	ds_read_b64_tr_b16 v[118:119], v200 offset:34304
	ds_read_b128 v[184:187], v160 offset:2048
	ds_read_b128 v[176:179], v160 offset:2560
	v_mfma_f32_32x32x16_bf16 v[32:47], v[148:151], v[120:123], v[32:47]
	v_exp_f32_e32 v86, v86
	v_exp_f32_e32 v87, v87
	ds_read_b64_tr_b16 v[120:121], v200 offset:37888
	ds_read_b64_tr_b16 v[122:123], v200 offset:38400
	ds_read_b128 v[172:175], v160 offset:4096
	ds_read_b128 v[168:171], v160 offset:4608
	s_waitcnt lgkmcnt(14)
	v_mfma_f32_32x32x16_bf16 v[48:63], v[152:155], v[124:127], v[48:63]
	v_exp_f32_e32 v88, v88
	v_exp_f32_e32 v89, v89
	ds_read_b64_tr_b16 v[124:125], v200 offset:34816
	ds_read_b64_tr_b16 v[126:127], v200 offset:35328
	ds_read_b128 v[164:167], v160 offset:6144
	ds_read_b128 v[160:163], v160 offset:6656
	v_mfma_f32_32x32x16_bf16 v[32:47], v[152:155], v[96:99], v[32:47]
	v_exp_f32_e32 v90, v90
	v_exp_f32_e32 v91, v91
	ds_read_b64_tr_b16 v[96:97], v200 offset:38912
	ds_read_b64_tr_b16 v[98:99], v200 offset:39424
	v_mfma_f32_32x32x16_bf16 v[48:63], v[156:159], v[100:103], v[48:63]
	v_exp_f32_e32 v92, v92
	v_exp_f32_e32 v93, v93
	ds_read_b64_tr_b16 v[100:101], v200 offset:35840
	ds_read_b64_tr_b16 v[102:103], v200 offset:36352
	v_mfma_f32_32x32x16_bf16 v[32:47], v[156:159], v[104:107], v[32:47]
	v_exp_f32_e32 v94, v94
	v_exp_f32_e32 v95, v95
	ds_read_b64_tr_b16 v[104:105], v200 offset:39936
	ds_read_b64_tr_b16 v[106:107], v200 offset:40448
	s_waitcnt lgkmcnt(14)
	v_mfma_f32_32x32x16_bf16 v[16:31], v[144:147], v[108:111], v[16:31]
	v_exp_f32_e32 v64, v64
	v_exp_f32_e32 v65, v65
	v_mfma_f32_32x32x16_bf16 v[0:15], v[144:147], v[112:115], v[0:15]
	v_exp_f32_e32 v66, v66
	v_exp_f32_e32 v67, v67
	v_mfma_f32_32x32x16_bf16 v[16:31], v[148:151], v[116:119], v[16:31]
	v_exp_f32_e32 v68, v68
	v_exp_f32_e32 v69, v69
	s_waitcnt lgkmcnt(12)
	v_mfma_f32_32x32x16_bf16 v[0:15], v[148:151], v[120:123], v[0:15]
	v_exp_f32_e32 v70, v70
	v_exp_f32_e32 v71, v71
	s_waitcnt lgkmcnt(8)
	v_mfma_f32_32x32x16_bf16 v[16:31], v[152:155], v[124:127], v[16:31]
	v_exp_f32_e32 v72, v72
	v_exp_f32_e32 v73, v73
	s_waitcnt lgkmcnt(4)
	v_mfma_f32_32x32x16_bf16 v[0:15], v[152:155], v[96:99], v[0:15]
	v_exp_f32_e32 v74, v74
	v_exp_f32_e32 v75, v75
	s_waitcnt lgkmcnt(2)
	v_mfma_f32_32x32x16_bf16 v[16:31], v[156:159], v[100:103], v[16:31]
	v_exp_f32_e32 v76, v76
	v_exp_f32_e32 v77, v77
	s_waitcnt lgkmcnt(0)
	v_mfma_f32_32x32x16_bf16 v[0:15], v[156:159], v[104:107], v[0:15]
	v_exp_f32_e32 v78, v78
	v_exp_f32_e32 v79, v79
	s_add_i32 s37, s59, 0x2000
	s_cmpk_lg_i32 s59, 0x4000
	s_cselect_b32 s66, s37, 0
	s_add_i32 s39, s6, 2
	s_waitcnt vmcnt(3) lgkmcnt(0)
	s_barrier
	s_add_u32 s4, s4, 0x20000
	s_addc_u32 s5, s5, 0
	s_add_u32 s98, s98, 0x20000
	s_addc_u32 s99, s99, 0
	s_cmp_gt_u32 s39, s57
	s_mov_b32 s38, s36
	s_cbranch_scc0 .LBB0_439
	s_add_i32 s6, s6, -3
	s_branch .LBB0_443
